# th3 plus first K-loop iteration of each GEMM unit peeled with srcC=0, removing the 128 accumulator-zeroing v_mov per wave per unit (all three GEMM loops)
# speedup vs baseline: 1.0140x; 1.0140x over previous
.LBB0_255:
	s_ashr_i32 s17, s16, 31
	s_lshl_b64 s[8:9], s[16:17], 20
	v_readlane_b32 s18, v254, 39
	v_readlane_b32 s19, v254, 40
	s_add_u32 s18, s18, s8
	s_addc_u32 s19, s19, s9
	s_and_b64 s[8:9], s[36:37], exec
	s_cselect_b32 s8, s19, s3
	s_cselect_b32 s9, s18, s2
	s_ashr_i32 s15, s14, 31
	s_lshl_b64 s[20:21], s[14:15], 20
	s_add_u32 s20, s29, s20
	s_addc_u32 s21, s38, s21
	s_and_b64 s[26:27], s[36:37], exec
	s_cselect_b32 s15, s21, s23
	s_cselect_b32 s17, s20, s22
	s_add_u32 s2, s2, 0x80800
	s_addc_u32 s3, s3, 0
	s_add_u32 s33, s22, 0x100
	s_addc_u32 s34, s23, 0
	s_mov_b32 s35, -2
	s_add_u32 s22, s2, 0xfff80800
	s_addc_u32 s23, s3, -1
	s_add_i32 s48, 0, 0x10000
	s_cmp_eq_u32 s35, 28
	s_cselect_b32 s27, s8, s23
	s_cselect_b32 s26, s9, s22
	s_cselect_b32 s23, s15, s34
	s_cselect_b32 s22, s17, s33
	s_add_i32 s50, 0, 0x14000
	v_add_u32_e32 v176, s48, v191
	v_add_u32_e32 v188, s50, v191
	ds_read_b128 v[148:151], v176
	ds_read_b128 v[152:155], v176 offset:1024
	ds_read_b128 v[172:175], v176 offset:2048
	ds_read_b128 v[176:179], v176 offset:3072
	ds_read_b128 v[180:183], v188
	ds_read_b128 v[184:187], v188 offset:1024
	ds_read_b128 v[196:199], v188 offset:2048
	ds_read_b128 v[200:203], v188 offset:3072
	s_add_i32 m0, s39, 0xc000
	ds_read_b128 v[204:207], v194
	ds_read_b128 v[212:215], v194 offset:1024
	ds_read_b128 v[216:219], v194 offset:2048
	ds_read_b128 v[220:223], v194 offset:3072
	ds_read_b128 v[224:227], v194 offset:4096
	ds_read_b128 v[228:231], v194 offset:5120
	ds_read_b128 v[232:235], v194 offset:6144
	ds_read_b128 v[236:239], v194 offset:7168
	global_load_lds_dwordx4 v168, s[2:3]
	s_add_i32 m0, s39, 0xe000
	s_nop 0
	global_load_lds_dwordx4 v170, s[2:3]
	s_waitcnt vmcnt(8)
	s_waitcnt lgkmcnt(0)
	s_barrier
	s_setprio 1
	s_waitcnt lgkmcnt(0)
	v_mfma_f32_16x16x32_bf16 v[144:147], v[148:151], v[204:207], 0
	v_mfma_f32_16x16x32_bf16 v[136:139], v[172:175], v[204:207], 0
	v_mfma_f32_16x16x32_bf16 v[128:131], v[148:151], v[216:219], 0
	v_mfma_f32_16x16x32_bf16 v[120:123], v[172:175], v[216:219], 0
	v_mfma_f32_16x16x32_bf16 v[112:115], v[148:151], v[224:227], 0
	v_mfma_f32_16x16x32_bf16 v[104:107], v[172:175], v[224:227], 0
	v_mfma_f32_16x16x32_bf16 v[96:99], v[148:151], v[232:235], 0
	v_mfma_f32_16x16x32_bf16 v[88:91], v[172:175], v[232:235], 0
	v_mfma_f32_16x16x32_bf16 v[144:147], v[152:155], v[212:215], v[144:147]
	v_mfma_f32_16x16x32_bf16 v[136:139], v[176:179], v[212:215], v[136:139]
	v_mfma_f32_16x16x32_bf16 v[128:131], v[152:155], v[220:223], v[128:131]
	v_mfma_f32_16x16x32_bf16 v[120:123], v[176:179], v[220:223], v[120:123]
	v_mfma_f32_16x16x32_bf16 v[112:115], v[152:155], v[228:231], v[112:115]
	v_mfma_f32_16x16x32_bf16 v[104:107], v[176:179], v[228:231], v[104:107]
	v_mfma_f32_16x16x32_bf16 v[96:99], v[152:155], v[236:239], v[96:99]
	v_mfma_f32_16x16x32_bf16 v[88:91], v[176:179], v[236:239], v[88:91]
	s_setprio 0
	s_setprio 1
	v_mfma_f32_16x16x32_bf16 v[140:143], v[180:183], v[204:207], 0
	v_mfma_f32_16x16x32_bf16 v[132:135], v[196:199], v[204:207], 0
	v_mfma_f32_16x16x32_bf16 v[124:127], v[180:183], v[216:219], 0
	v_mfma_f32_16x16x32_bf16 v[116:119], v[196:199], v[216:219], 0
	v_mfma_f32_16x16x32_bf16 v[108:111], v[180:183], v[224:227], 0
	v_mfma_f32_16x16x32_bf16 v[100:103], v[196:199], v[224:227], 0
	v_mfma_f32_16x16x32_bf16 v[92:95], v[180:183], v[232:235], 0
	v_mfma_f32_16x16x32_bf16 v[84:87], v[196:199], v[232:235], 0
	v_mfma_f32_16x16x32_bf16 v[140:143], v[184:187], v[212:215], v[140:143]
	v_mfma_f32_16x16x32_bf16 v[132:135], v[200:203], v[212:215], v[132:135]
	v_mfma_f32_16x16x32_bf16 v[124:127], v[184:187], v[220:223], v[124:127]
	v_mfma_f32_16x16x32_bf16 v[116:119], v[200:203], v[220:223], v[116:119]
	v_mfma_f32_16x16x32_bf16 v[108:111], v[184:187], v[228:231], v[108:111]
	v_mfma_f32_16x16x32_bf16 v[100:103], v[200:203], v[228:231], v[100:103]
	v_mfma_f32_16x16x32_bf16 v[92:95], v[184:187], v[236:239], v[92:95]
	v_mfma_f32_16x16x32_bf16 v[84:87], v[200:203], v[236:239], v[84:87]
	s_setprio 0
	s_barrier
	s_add_i32 s48, s48, s28
	s_add_u32 s98, s22, 0x80
	s_addc_u32 s99, s23, 0
	s_add_u32 s100, s26, 0x800
	s_addc_u32 s101, s27, 0
	s_mov_b32 m0, s48
	ds_read_b128 v[204:207], v194 offset:16384
	ds_read_b128 v[212:215], v194 offset:17408
	ds_read_b128 v[216:219], v194 offset:18432
	ds_read_b128 v[220:223], v194 offset:19456
	ds_read_b128 v[224:227], v194 offset:20480
	ds_read_b128 v[228:231], v194 offset:21504
	ds_read_b128 v[232:235], v194 offset:22528
	ds_read_b128 v[236:239], v194 offset:23552
	global_load_lds_dwordx4 v2, s[22:23]
	s_add_i32 m0, s48, 0x2000
	s_add_u32 s48, s22, 0x80000
	s_addc_u32 s49, s23, 0
	s_add_i32 s50, s50, s28
	global_load_lds_dwordx4 v156, s[22:23]
	s_mov_b32 m0, s50
	s_nop 0
	global_load_lds_dwordx4 v2, s[48:49]
	s_add_i32 m0, s50, 0x2000
	s_nop 0
	global_load_lds_dwordx4 v156, s[48:49]
	s_mov_b32 m0, s39
	s_nop 0
	global_load_lds_dwordx4 v160, s[26:27]
	s_mov_b32 m0, s41
	s_nop 0
	global_load_lds_dwordx4 v158, s[26:27]
	s_waitcnt vmcnt(8)
	s_waitcnt lgkmcnt(0)
	s_barrier
	s_setprio 1
	s_waitcnt lgkmcnt(0)
	v_mfma_f32_16x16x32_bf16 v[80:83], v[148:151], v[204:207], 0
	v_mfma_f32_16x16x32_bf16 v[72:75], v[172:175], v[204:207], 0
	v_mfma_f32_16x16x32_bf16 v[64:67], v[148:151], v[216:219], 0
	v_mfma_f32_16x16x32_bf16 v[56:59], v[172:175], v[216:219], 0
	v_mfma_f32_16x16x32_bf16 v[48:51], v[148:151], v[224:227], 0
	v_mfma_f32_16x16x32_bf16 v[40:43], v[172:175], v[224:227], 0
	v_mfma_f32_16x16x32_bf16 v[32:35], v[148:151], v[232:235], 0
	v_mfma_f32_16x16x32_bf16 v[24:27], v[172:175], v[232:235], 0
	v_mfma_f32_16x16x32_bf16 v[80:83], v[152:155], v[212:215], v[80:83]
	v_mfma_f32_16x16x32_bf16 v[72:75], v[176:179], v[212:215], v[72:75]
	v_mfma_f32_16x16x32_bf16 v[64:67], v[152:155], v[220:223], v[64:67]
	v_mfma_f32_16x16x32_bf16 v[56:59], v[176:179], v[220:223], v[56:59]
	v_mfma_f32_16x16x32_bf16 v[48:51], v[152:155], v[228:231], v[48:51]
	v_mfma_f32_16x16x32_bf16 v[40:43], v[176:179], v[228:231], v[40:43]
	v_mfma_f32_16x16x32_bf16 v[32:35], v[152:155], v[236:239], v[32:35]
	v_mfma_f32_16x16x32_bf16 v[24:27], v[176:179], v[236:239], v[24:27]
	s_setprio 0
	s_setprio 1
	v_mfma_f32_16x16x32_bf16 v[76:79], v[180:183], v[204:207], 0
	v_mfma_f32_16x16x32_bf16 v[68:71], v[196:199], v[204:207], 0
	v_mfma_f32_16x16x32_bf16 v[60:63], v[180:183], v[216:219], 0
	v_mfma_f32_16x16x32_bf16 v[52:55], v[196:199], v[216:219], 0
	v_mfma_f32_16x16x32_bf16 v[44:47], v[180:183], v[224:227], 0
	v_mfma_f32_16x16x32_bf16 v[36:39], v[196:199], v[224:227], 0
	v_mfma_f32_16x16x32_bf16 v[28:31], v[180:183], v[232:235], 0
	v_mfma_f32_16x16x32_bf16 v[20:23], v[196:199], v[232:235], 0
	v_mfma_f32_16x16x32_bf16 v[76:79], v[184:187], v[212:215], v[76:79]
	v_mfma_f32_16x16x32_bf16 v[68:71], v[200:203], v[212:215], v[68:71]
	v_mfma_f32_16x16x32_bf16 v[60:63], v[184:187], v[220:223], v[60:63]
	v_mfma_f32_16x16x32_bf16 v[52:55], v[200:203], v[220:223], v[52:55]
	v_mfma_f32_16x16x32_bf16 v[44:47], v[184:187], v[228:231], v[44:47]
	v_mfma_f32_16x16x32_bf16 v[36:39], v[200:203], v[228:231], v[36:39]
	v_mfma_f32_16x16x32_bf16 v[28:31], v[184:187], v[236:239], v[28:31]
	v_mfma_f32_16x16x32_bf16 v[20:23], v[200:203], v[236:239], v[20:23]
	s_setprio 0
	s_barrier
	s_add_i32 s48, 0, 0x18000
	s_add_i32 s49, 0, 0x1c000
	v_add_u32_e32 v176, s48, v191
	v_add_u32_e32 v195, s49, v191
	ds_read_b128 v[148:151], v176
	ds_read_b128 v[152:155], v176 offset:1024
	ds_read_b128 v[172:175], v176 offset:2048
	ds_read_b128 v[176:179], v176 offset:3072
	ds_read_b128 v[180:183], v195
	ds_read_b128 v[184:187], v195 offset:1024
	ds_read_b128 v[196:199], v195 offset:2048
	ds_read_b128 v[200:203], v195 offset:3072
	s_add_u32 s26, s26, 0x80000
	s_addc_u32 s27, s27, 0
	s_mov_b32 m0, s42
	ds_read_b128 v[204:207], v194 offset:32768
	ds_read_b128 v[212:215], v194 offset:33792
	ds_read_b128 v[216:219], v194 offset:34816
	ds_read_b128 v[220:223], v194 offset:35840
	ds_read_b128 v[224:227], v194 offset:36864
	ds_read_b128 v[228:231], v194 offset:37888
	ds_read_b128 v[232:235], v194 offset:38912
	ds_read_b128 v[236:239], v194 offset:39936
	global_load_lds_dwordx4 v160, s[26:27]
	s_mov_b32 m0, s43
	s_nop 0
	global_load_lds_dwordx4 v158, s[26:27]
	s_waitcnt vmcnt(8)
	s_waitcnt lgkmcnt(0)
	s_barrier
	s_setprio 1
	s_waitcnt lgkmcnt(0)
	v_mfma_f32_16x16x32_bf16 v[144:147], v[148:151], v[204:207], v[144:147]
	v_mfma_f32_16x16x32_bf16 v[136:139], v[172:175], v[204:207], v[136:139]
	v_mfma_f32_16x16x32_bf16 v[128:131], v[148:151], v[216:219], v[128:131]
	v_mfma_f32_16x16x32_bf16 v[120:123], v[172:175], v[216:219], v[120:123]
	v_mfma_f32_16x16x32_bf16 v[112:115], v[148:151], v[224:227], v[112:115]
	v_mfma_f32_16x16x32_bf16 v[104:107], v[172:175], v[224:227], v[104:107]
	v_mfma_f32_16x16x32_bf16 v[96:99], v[148:151], v[232:235], v[96:99]
	v_mfma_f32_16x16x32_bf16 v[88:91], v[172:175], v[232:235], v[88:91]
	v_mfma_f32_16x16x32_bf16 v[144:147], v[152:155], v[212:215], v[144:147]
	v_mfma_f32_16x16x32_bf16 v[136:139], v[176:179], v[212:215], v[136:139]
	v_mfma_f32_16x16x32_bf16 v[128:131], v[152:155], v[220:223], v[128:131]
	v_mfma_f32_16x16x32_bf16 v[120:123], v[176:179], v[220:223], v[120:123]
	v_mfma_f32_16x16x32_bf16 v[112:115], v[152:155], v[228:231], v[112:115]
	v_mfma_f32_16x16x32_bf16 v[104:107], v[176:179], v[228:231], v[104:107]
	v_mfma_f32_16x16x32_bf16 v[96:99], v[152:155], v[236:239], v[96:99]
	v_mfma_f32_16x16x32_bf16 v[88:91], v[176:179], v[236:239], v[88:91]
	s_setprio 0
	s_setprio 1
	v_mfma_f32_16x16x32_bf16 v[140:143], v[180:183], v[204:207], v[140:143]
	v_mfma_f32_16x16x32_bf16 v[132:135], v[196:199], v[204:207], v[132:135]
	v_mfma_f32_16x16x32_bf16 v[124:127], v[180:183], v[216:219], v[124:127]
	v_mfma_f32_16x16x32_bf16 v[116:119], v[196:199], v[216:219], v[116:119]
	v_mfma_f32_16x16x32_bf16 v[108:111], v[180:183], v[224:227], v[108:111]
	v_mfma_f32_16x16x32_bf16 v[100:103], v[196:199], v[224:227], v[100:103]
	v_mfma_f32_16x16x32_bf16 v[92:95], v[180:183], v[232:235], v[92:95]
	v_mfma_f32_16x16x32_bf16 v[84:87], v[196:199], v[232:235], v[84:87]
	v_mfma_f32_16x16x32_bf16 v[140:143], v[184:187], v[212:215], v[140:143]
	v_mfma_f32_16x16x32_bf16 v[132:135], v[200:203], v[212:215], v[132:135]
	v_mfma_f32_16x16x32_bf16 v[124:127], v[184:187], v[220:223], v[124:127]
	v_mfma_f32_16x16x32_bf16 v[116:119], v[200:203], v[220:223], v[116:119]
	v_mfma_f32_16x16x32_bf16 v[108:111], v[184:187], v[228:231], v[108:111]
	v_mfma_f32_16x16x32_bf16 v[100:103], v[200:203], v[228:231], v[100:103]
	v_mfma_f32_16x16x32_bf16 v[92:95], v[184:187], v[236:239], v[92:95]
	v_mfma_f32_16x16x32_bf16 v[84:87], v[200:203], v[236:239], v[84:87]
	s_setprio 0
	s_barrier
	s_add_i32 s26, s48, s28
	s_mov_b32 m0, s26
	ds_read_b128 v[204:207], v194 offset:49152
	ds_read_b128 v[212:215], v194 offset:50176
	ds_read_b128 v[216:219], v194 offset:51200
	ds_read_b128 v[220:223], v194 offset:52224
	ds_read_b128 v[224:227], v194 offset:53248
	ds_read_b128 v[228:231], v194 offset:54272
	ds_read_b128 v[232:235], v194 offset:55296
	ds_read_b128 v[236:239], v194 offset:56320
	global_load_lds_dwordx4 v2, s[98:99]
	s_add_i32 m0, s26, 0x2000
	s_add_u32 s22, s22, 0x80080
	s_addc_u32 s23, s23, 0
	s_add_i32 s26, s49, s28
	global_load_lds_dwordx4 v156, s[98:99]
	s_mov_b32 m0, s26
	s_nop 0
	global_load_lds_dwordx4 v2, s[22:23]
	s_add_i32 m0, s26, 0x2000
	s_nop 0
	global_load_lds_dwordx4 v156, s[22:23]
	s_mov_b32 m0, s44
	s_nop 0
	global_load_lds_dwordx4 v160, s[100:101]
	s_mov_b32 m0, s45
	s_nop 0
	global_load_lds_dwordx4 v158, s[100:101]
	s_waitcnt vmcnt(8)
	s_waitcnt lgkmcnt(0)
	s_barrier
	s_setprio 1
	s_waitcnt lgkmcnt(0)
	v_mfma_f32_16x16x32_bf16 v[80:83], v[148:151], v[204:207], v[80:83]
	v_mfma_f32_16x16x32_bf16 v[72:75], v[172:175], v[204:207], v[72:75]
	v_mfma_f32_16x16x32_bf16 v[64:67], v[148:151], v[216:219], v[64:67]
	v_mfma_f32_16x16x32_bf16 v[56:59], v[172:175], v[216:219], v[56:59]
	v_mfma_f32_16x16x32_bf16 v[48:51], v[148:151], v[224:227], v[48:51]
	v_mfma_f32_16x16x32_bf16 v[40:43], v[172:175], v[224:227], v[40:43]
	v_mfma_f32_16x16x32_bf16 v[32:35], v[148:151], v[232:235], v[32:35]
	v_mfma_f32_16x16x32_bf16 v[24:27], v[172:175], v[232:235], v[24:27]
	v_mfma_f32_16x16x32_bf16 v[80:83], v[152:155], v[212:215], v[80:83]
	v_mfma_f32_16x16x32_bf16 v[72:75], v[176:179], v[212:215], v[72:75]
	v_mfma_f32_16x16x32_bf16 v[64:67], v[152:155], v[220:223], v[64:67]
	v_mfma_f32_16x16x32_bf16 v[56:59], v[176:179], v[220:223], v[56:59]
	v_mfma_f32_16x16x32_bf16 v[48:51], v[152:155], v[228:231], v[48:51]
	v_mfma_f32_16x16x32_bf16 v[40:43], v[176:179], v[228:231], v[40:43]
	v_mfma_f32_16x16x32_bf16 v[32:35], v[152:155], v[236:239], v[32:35]
	v_mfma_f32_16x16x32_bf16 v[24:27], v[176:179], v[236:239], v[24:27]
	s_setprio 0
	s_setprio 1
	v_mfma_f32_16x16x32_bf16 v[76:79], v[180:183], v[204:207], v[76:79]
	v_mfma_f32_16x16x32_bf16 v[68:71], v[196:199], v[204:207], v[68:71]
	v_mfma_f32_16x16x32_bf16 v[60:63], v[180:183], v[216:219], v[60:63]
	v_mfma_f32_16x16x32_bf16 v[52:55], v[196:199], v[216:219], v[52:55]
	v_mfma_f32_16x16x32_bf16 v[44:47], v[180:183], v[224:227], v[44:47]
	v_mfma_f32_16x16x32_bf16 v[36:39], v[196:199], v[224:227], v[36:39]
	v_mfma_f32_16x16x32_bf16 v[28:31], v[180:183], v[232:235], v[28:31]
	v_mfma_f32_16x16x32_bf16 v[20:23], v[196:199], v[232:235], v[20:23]
	v_mfma_f32_16x16x32_bf16 v[76:79], v[184:187], v[212:215], v[76:79]
	v_mfma_f32_16x16x32_bf16 v[68:71], v[200:203], v[212:215], v[68:71]
	v_mfma_f32_16x16x32_bf16 v[60:63], v[184:187], v[220:223], v[60:63]
	v_mfma_f32_16x16x32_bf16 v[52:55], v[200:203], v[220:223], v[52:55]
	v_mfma_f32_16x16x32_bf16 v[44:47], v[184:187], v[228:231], v[44:47]
	v_mfma_f32_16x16x32_bf16 v[36:39], v[200:203], v[228:231], v[36:39]
	v_mfma_f32_16x16x32_bf16 v[28:31], v[184:187], v[236:239], v[28:31]
	v_mfma_f32_16x16x32_bf16 v[20:23], v[200:203], v[236:239], v[20:23]
	s_setprio 0
	s_barrier
	s_add_i32 s35, s35, 2
	s_add_u32 s2, s2, 0x1000
	s_addc_u32 s3, s3, 0
	s_add_u32 s33, s33, 0x100
	s_addc_u32 s34, s34, 0
	s_cmp_gt_u32 s35, 29
	s_cbranch_scc0 .LBB0_256
	s_branch .Lpeel_done_256

.Lpeel_done_256:
	s_and_b64 vcc, exec, s[12:13]
	s_cbranch_vccz .LBB0_259
	s_barrier

.LBB0_488:
	s_ashr_i32 s17, s16, 31
	s_lshl_b64 s[8:9], s[16:17], 20
	v_readlane_b32 s18, v254, 39
	v_readlane_b32 s19, v254, 40
	s_add_u32 s18, s18, s8
	s_addc_u32 s19, s19, s9
	s_and_b64 s[8:9], s[36:37], exec
	s_cselect_b32 s3, s19, s23
	s_cselect_b32 s6, s18, s22
	s_ashr_i32 s15, s14, 31
	s_lshl_b64 s[8:9], s[14:15], 20
	s_add_u32 s20, s28, s8
	s_addc_u32 s21, s29, s9
	s_and_b64 s[8:9], s[36:37], exec
	s_cselect_b32 s8, s21, s27
	s_cselect_b32 s9, s20, s26
	s_add_u32 s22, s22, 0x80800
	s_addc_u32 s23, s23, 0
	s_add_u32 s15, s26, 0x100
	s_addc_u32 s17, s27, 0
	s_mov_b32 s33, -2
	s_add_u32 s26, s22, 0xfff80800
	s_addc_u32 s27, s23, -1
	s_add_i32 s34, 0, 0x10000
	s_cmp_eq_u32 s33, 28
	s_cselect_b32 s39, s3, s27
	s_cselect_b32 s38, s6, s26
	s_cselect_b32 s27, s8, s17
	s_cselect_b32 s26, s9, s15
	s_add_i32 s53, 0, 0x14000
	v_add_u32_e32 v144, s34, v168
	v_add_u32_e32 v160, s53, v168
	ds_read_b128 v[4:7], v144
	ds_read_b128 v[8:11], v144 offset:1024
	ds_read_b128 v[140:143], v144 offset:2048
	ds_read_b128 v[144:147], v144 offset:3072
	ds_read_b128 v[172:175], v160
	ds_read_b128 v[176:179], v160 offset:1024
	ds_read_b128 v[180:183], v160 offset:2048
	ds_read_b128 v[184:187], v160 offset:3072
	s_add_i32 m0, s13, 0xc000
	ds_read_b128 v[188:191], v170
	ds_read_b128 v[192:195], v170 offset:1024
	ds_read_b128 v[196:199], v170 offset:2048
	ds_read_b128 v[200:203], v170 offset:3072
	ds_read_b128 v[204:207], v170 offset:4096
	ds_read_b128 v[212:215], v170 offset:5120
	ds_read_b128 v[216:219], v170 offset:6144
	ds_read_b128 v[220:223], v170 offset:7168
	global_load_lds_dwordx4 v156, s[22:23]
	s_add_i32 m0, s13, 0xe000
	s_nop 0
	global_load_lds_dwordx4 v158, s[22:23]
	s_waitcnt vmcnt(8)
	s_waitcnt lgkmcnt(0)
	s_barrier
	s_setprio 1
	s_waitcnt lgkmcnt(0)
	v_mfma_f32_16x16x32_bf16 v[136:139], v[4:7], v[188:191], 0
	v_mfma_f32_16x16x32_bf16 v[132:135], v[140:143], v[188:191], 0
	v_mfma_f32_16x16x32_bf16 v[128:131], v[4:7], v[196:199], 0
	v_mfma_f32_16x16x32_bf16 v[120:123], v[140:143], v[196:199], 0
	v_mfma_f32_16x16x32_bf16 v[112:115], v[4:7], v[204:207], 0
	v_mfma_f32_16x16x32_bf16 v[104:107], v[140:143], v[204:207], 0
	v_mfma_f32_16x16x32_bf16 v[96:99], v[4:7], v[216:219], 0
	v_mfma_f32_16x16x32_bf16 v[88:91], v[140:143], v[216:219], 0
	v_mfma_f32_16x16x32_bf16 v[136:139], v[8:11], v[192:195], v[136:139]
	v_mfma_f32_16x16x32_bf16 v[132:135], v[144:147], v[192:195], v[132:135]
	v_mfma_f32_16x16x32_bf16 v[128:131], v[8:11], v[200:203], v[128:131]
	v_mfma_f32_16x16x32_bf16 v[120:123], v[144:147], v[200:203], v[120:123]
	v_mfma_f32_16x16x32_bf16 v[112:115], v[8:11], v[212:215], v[112:115]
	v_mfma_f32_16x16x32_bf16 v[104:107], v[144:147], v[212:215], v[104:107]
	v_mfma_f32_16x16x32_bf16 v[96:99], v[8:11], v[220:223], v[96:99]
	v_mfma_f32_16x16x32_bf16 v[88:91], v[144:147], v[220:223], v[88:91]
	s_setprio 0
	s_setprio 1
	v_mfma_f32_16x16x32_bf16 v[124:127], v[172:175], v[188:191], 0
	v_mfma_f32_16x16x32_bf16 v[116:119], v[180:183], v[188:191], 0
	v_mfma_f32_16x16x32_bf16 v[108:111], v[172:175], v[196:199], 0
	v_mfma_f32_16x16x32_bf16 v[100:103], v[180:183], v[196:199], 0
	v_mfma_f32_16x16x32_bf16 v[92:95], v[172:175], v[204:207], 0
	v_mfma_f32_16x16x32_bf16 v[84:87], v[180:183], v[204:207], 0
	v_mfma_f32_16x16x32_bf16 v[80:83], v[172:175], v[216:219], 0
	v_mfma_f32_16x16x32_bf16 v[76:79], v[180:183], v[216:219], 0
	v_mfma_f32_16x16x32_bf16 v[124:127], v[176:179], v[192:195], v[124:127]
	v_mfma_f32_16x16x32_bf16 v[116:119], v[184:187], v[192:195], v[116:119]
	v_mfma_f32_16x16x32_bf16 v[108:111], v[176:179], v[200:203], v[108:111]
	v_mfma_f32_16x16x32_bf16 v[100:103], v[184:187], v[200:203], v[100:103]
	v_mfma_f32_16x16x32_bf16 v[92:95], v[176:179], v[212:215], v[92:95]
	v_mfma_f32_16x16x32_bf16 v[84:87], v[184:187], v[212:215], v[84:87]
	v_mfma_f32_16x16x32_bf16 v[80:83], v[176:179], v[220:223], v[80:83]
	v_mfma_f32_16x16x32_bf16 v[76:79], v[184:187], v[220:223], v[76:79]
	s_setprio 0
	s_barrier
	s_add_i32 s34, s34, s7
	s_add_u32 s98, s26, 0x80
	s_addc_u32 s99, s27, 0
	s_add_u32 s100, s38, 0x800
	s_addc_u32 s101, s39, 0
	s_mov_b32 m0, s34
	ds_read_b128 v[188:191], v170 offset:16384
	ds_read_b128 v[192:195], v170 offset:17408
	ds_read_b128 v[196:199], v170 offset:18432
	ds_read_b128 v[200:203], v170 offset:19456
	ds_read_b128 v[204:207], v170 offset:20480
	ds_read_b128 v[212:215], v170 offset:21504
	ds_read_b128 v[216:219], v170 offset:22528
	ds_read_b128 v[220:223], v170 offset:23552
	global_load_lds_dwordx4 v2, s[26:27]
	s_add_i32 m0, s34, 0x2000
	s_add_u32 s34, s26, 0x80000
	s_addc_u32 s35, s27, 0
	s_add_i32 s53, s53, s7
	global_load_lds_dwordx4 v148, s[26:27]
	s_mov_b32 m0, s53
	s_nop 0
	global_load_lds_dwordx4 v2, s[34:35]
	s_add_i32 m0, s53, 0x2000
	s_nop 0
	global_load_lds_dwordx4 v148, s[34:35]
	s_mov_b32 m0, s13
	s_nop 0
	global_load_lds_dwordx4 v152, s[38:39]
	s_mov_b32 m0, s46
	s_nop 0
	global_load_lds_dwordx4 v150, s[38:39]
	s_waitcnt vmcnt(8)
	s_waitcnt lgkmcnt(0)
	s_barrier
	s_setprio 1
	s_waitcnt lgkmcnt(0)
	v_mfma_f32_16x16x32_bf16 v[72:75], v[4:7], v[188:191], 0
	v_mfma_f32_16x16x32_bf16 v[68:71], v[140:143], v[188:191], 0
	v_mfma_f32_16x16x32_bf16 v[64:67], v[4:7], v[196:199], 0
	v_mfma_f32_16x16x32_bf16 v[56:59], v[140:143], v[196:199], 0
	v_mfma_f32_16x16x32_bf16 v[48:51], v[4:7], v[204:207], 0
	v_mfma_f32_16x16x32_bf16 v[40:43], v[140:143], v[204:207], 0
	v_mfma_f32_16x16x32_bf16 v[4:7], v[4:7], v[216:219], 0
	v_mfma_f32_16x16x32_bf16 v[72:75], v[8:11], v[192:195], v[72:75]
	v_mfma_f32_16x16x32_bf16 v[68:71], v[144:147], v[192:195], v[68:71]
	v_mfma_f32_16x16x32_bf16 v[64:67], v[8:11], v[200:203], v[64:67]
	v_mfma_f32_16x16x32_bf16 v[56:59], v[144:147], v[200:203], v[56:59]
	v_mfma_f32_16x16x32_bf16 v[48:51], v[8:11], v[212:215], v[48:51]
	v_mfma_f32_16x16x32_bf16 v[40:43], v[144:147], v[212:215], v[40:43]
	v_mfma_f32_16x16x32_bf16 v[4:7], v[8:11], v[220:223], v[4:7]
	v_mfma_f32_16x16x32_bf16 v[8:11], v[140:143], v[216:219], 0
	v_mfma_f32_16x16x32_bf16 v[8:11], v[144:147], v[220:223], v[8:11]
	s_setprio 0
	s_setprio 1
	v_mfma_f32_16x16x32_bf16 v[24:27], v[172:175], v[188:191], 0
	v_mfma_f32_16x16x32_bf16 v[60:63], v[176:179], v[192:195], v[24:27]
	v_mfma_f32_16x16x32_bf16 v[24:27], v[180:183], v[188:191], 0
	v_mfma_f32_16x16x32_bf16 v[52:55], v[184:187], v[192:195], v[24:27]
	v_mfma_f32_16x16x32_bf16 v[24:27], v[172:175], v[196:199], 0
	v_mfma_f32_16x16x32_bf16 v[44:47], v[176:179], v[200:203], v[24:27]
	v_mfma_f32_16x16x32_bf16 v[24:27], v[180:183], v[196:199], 0
	v_mfma_f32_16x16x32_bf16 v[36:39], v[184:187], v[200:203], v[24:27]
	v_mfma_f32_16x16x32_bf16 v[24:27], v[172:175], v[204:207], 0
	v_mfma_f32_16x16x32_bf16 v[20:23], v[180:183], v[204:207], 0
	v_mfma_f32_16x16x32_bf16 v[16:19], v[172:175], v[216:219], 0
	v_mfma_f32_16x16x32_bf16 v[12:15], v[180:183], v[216:219], 0
	v_mfma_f32_16x16x32_bf16 v[28:31], v[176:179], v[212:215], v[24:27]
	v_mfma_f32_16x16x32_bf16 v[20:23], v[184:187], v[212:215], v[20:23]
	v_mfma_f32_16x16x32_bf16 v[16:19], v[176:179], v[220:223], v[16:19]
	v_mfma_f32_16x16x32_bf16 v[12:15], v[184:187], v[220:223], v[12:15]
	s_setprio 0
	s_barrier
	s_add_i32 s53, 0, 0x18000
	s_add_i32 s54, 0, 0x1c000
	v_add_u32_e32 v144, s53, v168
	v_add_u32_e32 v171, s54, v168
	ds_read_b128 v[24:27], v144
	ds_read_b128 v[32:35], v144 offset:1024
	ds_read_b128 v[140:143], v144 offset:2048
	ds_read_b128 v[144:147], v144 offset:3072
	ds_read_b128 v[172:175], v171
	ds_read_b128 v[176:179], v171 offset:1024
	ds_read_b128 v[180:183], v171 offset:2048
	ds_read_b128 v[184:187], v171 offset:3072
	s_add_u32 s34, s38, 0x80000
	s_addc_u32 s35, s39, 0
	s_mov_b32 m0, s47
	ds_read_b128 v[188:191], v170 offset:32768
	ds_read_b128 v[192:195], v170 offset:33792
	ds_read_b128 v[196:199], v170 offset:34816
	ds_read_b128 v[200:203], v170 offset:35840
	ds_read_b128 v[204:207], v170 offset:36864
	ds_read_b128 v[212:215], v170 offset:37888
	ds_read_b128 v[216:219], v170 offset:38912
	ds_read_b128 v[220:223], v170 offset:39936
	global_load_lds_dwordx4 v152, s[34:35]
	s_mov_b32 m0, s48
	s_nop 0
	global_load_lds_dwordx4 v150, s[34:35]
	s_waitcnt vmcnt(8)
	s_waitcnt lgkmcnt(0)
	s_barrier
	s_setprio 1
	s_waitcnt lgkmcnt(0)
	v_mfma_f32_16x16x32_bf16 v[136:139], v[24:27], v[188:191], v[136:139]
	v_mfma_f32_16x16x32_bf16 v[132:135], v[140:143], v[188:191], v[132:135]
	v_mfma_f32_16x16x32_bf16 v[128:131], v[24:27], v[196:199], v[128:131]
	v_mfma_f32_16x16x32_bf16 v[120:123], v[140:143], v[196:199], v[120:123]
	v_mfma_f32_16x16x32_bf16 v[112:115], v[24:27], v[204:207], v[112:115]
	v_mfma_f32_16x16x32_bf16 v[104:107], v[140:143], v[204:207], v[104:107]
	v_mfma_f32_16x16x32_bf16 v[96:99], v[24:27], v[216:219], v[96:99]
	v_mfma_f32_16x16x32_bf16 v[88:91], v[140:143], v[216:219], v[88:91]
	v_mfma_f32_16x16x32_bf16 v[136:139], v[32:35], v[192:195], v[136:139]
	v_mfma_f32_16x16x32_bf16 v[132:135], v[144:147], v[192:195], v[132:135]
	v_mfma_f32_16x16x32_bf16 v[128:131], v[32:35], v[200:203], v[128:131]
	v_mfma_f32_16x16x32_bf16 v[120:123], v[144:147], v[200:203], v[120:123]
	v_mfma_f32_16x16x32_bf16 v[112:115], v[32:35], v[212:215], v[112:115]
	v_mfma_f32_16x16x32_bf16 v[104:107], v[144:147], v[212:215], v[104:107]
	v_mfma_f32_16x16x32_bf16 v[96:99], v[32:35], v[220:223], v[96:99]
	v_mfma_f32_16x16x32_bf16 v[88:91], v[144:147], v[220:223], v[88:91]
	s_setprio 0
	s_setprio 1
	v_mfma_f32_16x16x32_bf16 v[124:127], v[172:175], v[188:191], v[124:127]
	v_mfma_f32_16x16x32_bf16 v[116:119], v[180:183], v[188:191], v[116:119]
	v_mfma_f32_16x16x32_bf16 v[108:111], v[172:175], v[196:199], v[108:111]
	v_mfma_f32_16x16x32_bf16 v[100:103], v[180:183], v[196:199], v[100:103]
	v_mfma_f32_16x16x32_bf16 v[92:95], v[172:175], v[204:207], v[92:95]
	v_mfma_f32_16x16x32_bf16 v[84:87], v[180:183], v[204:207], v[84:87]
	v_mfma_f32_16x16x32_bf16 v[80:83], v[172:175], v[216:219], v[80:83]
	v_mfma_f32_16x16x32_bf16 v[76:79], v[180:183], v[216:219], v[76:79]
	v_mfma_f32_16x16x32_bf16 v[124:127], v[176:179], v[192:195], v[124:127]
	v_mfma_f32_16x16x32_bf16 v[116:119], v[184:187], v[192:195], v[116:119]
	v_mfma_f32_16x16x32_bf16 v[108:111], v[176:179], v[200:203], v[108:111]
	v_mfma_f32_16x16x32_bf16 v[100:103], v[184:187], v[200:203], v[100:103]
	v_mfma_f32_16x16x32_bf16 v[92:95], v[176:179], v[212:215], v[92:95]
	v_mfma_f32_16x16x32_bf16 v[84:87], v[184:187], v[212:215], v[84:87]
	v_mfma_f32_16x16x32_bf16 v[80:83], v[176:179], v[220:223], v[80:83]
	v_mfma_f32_16x16x32_bf16 v[76:79], v[184:187], v[220:223], v[76:79]
	s_setprio 0
	s_barrier
	s_add_i32 s34, s53, s7
	s_mov_b32 m0, s34
	ds_read_b128 v[188:191], v170 offset:49152
	ds_read_b128 v[192:195], v170 offset:50176
	ds_read_b128 v[196:199], v170 offset:51200
	ds_read_b128 v[200:203], v170 offset:52224
	ds_read_b128 v[204:207], v170 offset:53248
	ds_read_b128 v[212:215], v170 offset:54272
	ds_read_b128 v[216:219], v170 offset:55296
	ds_read_b128 v[220:223], v170 offset:56320
	global_load_lds_dwordx4 v2, s[98:99]
	s_add_i32 m0, s34, 0x2000
	s_add_u32 s26, s26, 0x80080
	s_addc_u32 s27, s27, 0
	s_add_i32 s34, s54, s7
	global_load_lds_dwordx4 v148, s[98:99]
	s_mov_b32 m0, s34
	s_nop 0
	global_load_lds_dwordx4 v2, s[26:27]
	s_add_i32 m0, s34, 0x2000
	s_nop 0
	global_load_lds_dwordx4 v148, s[26:27]
	s_mov_b32 m0, s49
	s_nop 0
	global_load_lds_dwordx4 v152, s[100:101]
	s_mov_b32 m0, s50
	s_nop 0
	global_load_lds_dwordx4 v150, s[100:101]
	s_waitcnt vmcnt(8)
	s_waitcnt lgkmcnt(0)
	s_barrier
	s_setprio 1
	s_waitcnt lgkmcnt(0)
	v_mfma_f32_16x16x32_bf16 v[72:75], v[24:27], v[188:191], v[72:75]
	v_mfma_f32_16x16x32_bf16 v[64:67], v[24:27], v[196:199], v[64:67]
	v_mfma_f32_16x16x32_bf16 v[48:51], v[24:27], v[204:207], v[48:51]
	v_mfma_f32_16x16x32_bf16 v[4:7], v[24:27], v[216:219], v[4:7]
	v_mfma_f32_16x16x32_bf16 v[72:75], v[32:35], v[192:195], v[72:75]
	v_mfma_f32_16x16x32_bf16 v[68:71], v[140:143], v[188:191], v[68:71]
	v_mfma_f32_16x16x32_bf16 v[64:67], v[32:35], v[200:203], v[64:67]
	v_mfma_f32_16x16x32_bf16 v[56:59], v[140:143], v[196:199], v[56:59]
	v_mfma_f32_16x16x32_bf16 v[48:51], v[32:35], v[212:215], v[48:51]
	v_mfma_f32_16x16x32_bf16 v[40:43], v[140:143], v[204:207], v[40:43]
	v_mfma_f32_16x16x32_bf16 v[32:35], v[32:35], v[220:223], v[4:7]
	v_mfma_f32_16x16x32_bf16 v[4:7], v[140:143], v[216:219], v[8:11]
	v_mfma_f32_16x16x32_bf16 v[68:71], v[144:147], v[192:195], v[68:71]
	v_mfma_f32_16x16x32_bf16 v[56:59], v[144:147], v[200:203], v[56:59]
	v_mfma_f32_16x16x32_bf16 v[40:43], v[144:147], v[212:215], v[40:43]
	v_mfma_f32_16x16x32_bf16 v[24:27], v[144:147], v[220:223], v[4:7]
	s_setprio 0
	s_setprio 1
	v_mfma_f32_16x16x32_bf16 v[4:7], v[172:175], v[188:191], v[60:63]
	v_mfma_f32_16x16x32_bf16 v[60:63], v[176:179], v[192:195], v[4:7]
	v_mfma_f32_16x16x32_bf16 v[4:7], v[180:183], v[188:191], v[52:55]
	v_mfma_f32_16x16x32_bf16 v[52:55], v[184:187], v[192:195], v[4:7]
	v_mfma_f32_16x16x32_bf16 v[4:7], v[172:175], v[196:199], v[44:47]
	v_mfma_f32_16x16x32_bf16 v[44:47], v[176:179], v[200:203], v[4:7]
	v_mfma_f32_16x16x32_bf16 v[4:7], v[180:183], v[196:199], v[36:39]
	v_mfma_f32_16x16x32_bf16 v[36:39], v[184:187], v[200:203], v[4:7]
	v_mfma_f32_16x16x32_bf16 v[4:7], v[172:175], v[204:207], v[28:31]
	v_mfma_f32_16x16x32_bf16 v[28:31], v[176:179], v[212:215], v[4:7]
	v_mfma_f32_16x16x32_bf16 v[4:7], v[180:183], v[204:207], v[20:23]
	v_mfma_f32_16x16x32_bf16 v[20:23], v[184:187], v[212:215], v[4:7]
	v_mfma_f32_16x16x32_bf16 v[4:7], v[172:175], v[216:219], v[16:19]
	v_mfma_f32_16x16x32_bf16 v[16:19], v[176:179], v[220:223], v[4:7]
	v_mfma_f32_16x16x32_bf16 v[4:7], v[180:183], v[216:219], v[12:15]
	v_mfma_f32_16x16x32_bf16 v[12:15], v[184:187], v[220:223], v[4:7]
	s_setprio 0
	s_barrier
	s_add_i32 s33, s33, 2
	s_add_u32 s22, s22, 0x1000
	s_addc_u32 s23, s23, 0
	s_add_u32 s15, s15, 0x100
	s_addc_u32 s17, s17, 0
	s_cmp_gt_u32 s33, 29
	s_cbranch_scc0 .LBB0_489
	s_branch .Lpeel_done_489

.Lpeel_done_489:
	s_and_b64 vcc, exec, s[4:5]
	s_cbranch_vccz .LBB0_492
	s_barrier

.LBB0_831:
	s_lshl_b32 s98, s100, 1
	s_add_u32 s2, s2, s100
	s_addc_u32 s3, s3, 0
	s_add_u32 s7, s22, 0x100
	s_addc_u32 s8, s23, 0
	s_mov_b32 s9, 0
	s_add_i32 s28, s9, 2
	s_add_u32 s22, s2, s100
	s_addc_u32 s23, s3, 0
	s_add_i32 s29, 0, 0x10000
	s_cmp_eq_u32 s52, s9
	s_cselect_b32 s23, s1, s23
	s_cselect_b32 s22, s0, s22
	v_add_u32_e32 v2, s29, v147
	s_cselect_b32 s35, s21, s8
	s_cselect_b32 s34, s20, s7
	s_add_i32 s9, 0, 0x14000
	ds_read_b128 v[152:155], v2
	ds_read_b128 v[156:159], v2 offset:1024
	ds_read_b128 v[160:163], v2 offset:2048
	ds_read_b128 v[168:171], v2 offset:3072
	v_add_u32_e32 v2, s9, v147
	ds_read_b128 v[172:175], v2
	ds_read_b128 v[176:179], v2 offset:1024
	ds_read_b128 v[180:183], v2 offset:2048
	ds_read_b128 v[184:187], v2 offset:3072
	s_add_i32 m0, s47, 0xc000
	ds_read_b128 v[188:191], v150
	ds_read_b128 v[192:195], v150 offset:1024
	ds_read_b128 v[196:199], v150 offset:2048
	ds_read_b128 v[200:203], v150 offset:3072
	ds_read_b128 v[204:207], v150 offset:4096
	ds_read_b128 v[210:213], v150 offset:5120
	ds_read_b128 v[214:217], v150 offset:6144
	ds_read_b128 v[218:221], v150 offset:7168
	global_load_lds_dwordx4 v140, s[2:3]
	s_add_i32 m0, s47, 0xe000
	s_nop 0
	global_load_lds_dwordx4 v142, s[2:3]
	s_waitcnt vmcnt(8)
	s_waitcnt lgkmcnt(0)
	s_barrier
	s_setprio 1
	s_waitcnt lgkmcnt(0)
	v_mfma_f32_16x16x32_bf16 v[128:131], v[152:155], v[188:191], 0
	v_mfma_f32_16x16x32_bf16 v[124:127], v[160:163], v[188:191], 0
	v_mfma_f32_16x16x32_bf16 v[112:115], v[152:155], v[196:199], 0
	v_mfma_f32_16x16x32_bf16 v[108:111], v[160:163], v[196:199], 0
	v_mfma_f32_16x16x32_bf16 v[96:99], v[152:155], v[204:207], 0
	v_mfma_f32_16x16x32_bf16 v[92:95], v[160:163], v[204:207], 0
	v_mfma_f32_16x16x32_bf16 v[80:83], v[152:155], v[214:217], 0
	v_mfma_f32_16x16x32_bf16 v[76:79], v[160:163], v[214:217], 0
	v_mfma_f32_16x16x32_bf16 v[128:131], v[156:159], v[192:195], v[128:131]
	v_mfma_f32_16x16x32_bf16 v[124:127], v[168:171], v[192:195], v[124:127]
	v_mfma_f32_16x16x32_bf16 v[112:115], v[156:159], v[200:203], v[112:115]
	v_mfma_f32_16x16x32_bf16 v[108:111], v[168:171], v[200:203], v[108:111]
	v_mfma_f32_16x16x32_bf16 v[96:99], v[156:159], v[210:213], v[96:99]
	v_mfma_f32_16x16x32_bf16 v[92:95], v[168:171], v[210:213], v[92:95]
	v_mfma_f32_16x16x32_bf16 v[80:83], v[156:159], v[218:221], v[80:83]
	v_mfma_f32_16x16x32_bf16 v[76:79], v[168:171], v[218:221], v[76:79]
	s_setprio 0
	s_setprio 1
	v_mfma_f32_16x16x32_bf16 v[120:123], v[172:175], v[188:191], 0
	v_mfma_f32_16x16x32_bf16 v[116:119], v[180:183], v[188:191], 0
	v_mfma_f32_16x16x32_bf16 v[104:107], v[172:175], v[196:199], 0
	v_mfma_f32_16x16x32_bf16 v[100:103], v[180:183], v[196:199], 0
	v_mfma_f32_16x16x32_bf16 v[88:91], v[172:175], v[204:207], 0
	v_mfma_f32_16x16x32_bf16 v[84:87], v[180:183], v[204:207], 0
	v_mfma_f32_16x16x32_bf16 v[72:75], v[172:175], v[214:217], 0
	v_mfma_f32_16x16x32_bf16 v[68:71], v[180:183], v[214:217], 0
	v_mfma_f32_16x16x32_bf16 v[120:123], v[176:179], v[192:195], v[120:123]
	v_mfma_f32_16x16x32_bf16 v[116:119], v[184:187], v[192:195], v[116:119]
	v_mfma_f32_16x16x32_bf16 v[104:107], v[176:179], v[200:203], v[104:107]
	v_mfma_f32_16x16x32_bf16 v[100:103], v[184:187], v[200:203], v[100:103]
	v_mfma_f32_16x16x32_bf16 v[88:91], v[176:179], v[210:213], v[88:91]
	v_mfma_f32_16x16x32_bf16 v[84:87], v[184:187], v[210:213], v[84:87]
	v_mfma_f32_16x16x32_bf16 v[72:75], v[176:179], v[218:221], v[72:75]
	v_mfma_f32_16x16x32_bf16 v[68:71], v[184:187], v[218:221], v[68:71]
	s_setprio 0
	s_barrier
	s_add_i32 s29, s29, s26
	s_mov_b32 m0, s29
	ds_read_b128 v[188:191], v150 offset:16384
	ds_read_b128 v[192:195], v150 offset:17408
	ds_read_b128 v[196:199], v150 offset:18432
	ds_read_b128 v[200:203], v150 offset:19456
	ds_read_b128 v[204:207], v150 offset:20480
	ds_read_b128 v[210:213], v150 offset:21504
	ds_read_b128 v[214:217], v150 offset:22528
	ds_read_b128 v[218:221], v150 offset:23552
	global_load_lds_dwordx4 v136, s[34:35]
	s_add_i32 m0, s29, 0x2000
	s_add_i32 s9, s9, s26
	global_load_lds_dwordx4 v132, s[34:35]
	s_add_u32 s34, s34, s16
	s_addc_u32 s35, s35, 0
	s_mov_b32 m0, s9
	s_nop 0
	global_load_lds_dwordx4 v136, s[34:35]
	s_add_i32 m0, s9, 0x2000
	s_nop 0
	global_load_lds_dwordx4 v132, s[34:35]
	s_mov_b32 m0, s47
	s_nop 0
	global_load_lds_dwordx4 v138, s[22:23]
	s_mov_b32 m0, s48
	s_nop 0
	global_load_lds_dwordx4 v134, s[22:23]
	s_waitcnt vmcnt(8)
	s_waitcnt lgkmcnt(0)
	s_barrier
	s_setprio 1
	s_waitcnt lgkmcnt(0)
	v_mfma_f32_16x16x32_bf16 v[64:67], v[152:155], v[188:191], 0
	v_mfma_f32_16x16x32_bf16 v[60:63], v[160:163], v[188:191], 0
	v_mfma_f32_16x16x32_bf16 v[48:51], v[152:155], v[196:199], 0
	v_mfma_f32_16x16x32_bf16 v[44:47], v[160:163], v[196:199], 0
	v_mfma_f32_16x16x32_bf16 v[32:35], v[152:155], v[204:207], 0
	v_mfma_f32_16x16x32_bf16 v[28:31], v[160:163], v[204:207], 0
	v_mfma_f32_16x16x32_bf16 v[16:19], v[152:155], v[214:217], 0
	v_mfma_f32_16x16x32_bf16 v[12:15], v[160:163], v[214:217], 0
	v_mfma_f32_16x16x32_bf16 v[64:67], v[156:159], v[192:195], v[64:67]
	v_mfma_f32_16x16x32_bf16 v[60:63], v[168:171], v[192:195], v[60:63]
	v_mfma_f32_16x16x32_bf16 v[48:51], v[156:159], v[200:203], v[48:51]
	v_mfma_f32_16x16x32_bf16 v[44:47], v[168:171], v[200:203], v[44:47]
	v_mfma_f32_16x16x32_bf16 v[32:35], v[156:159], v[210:213], v[32:35]
	v_mfma_f32_16x16x32_bf16 v[28:31], v[168:171], v[210:213], v[28:31]
	v_mfma_f32_16x16x32_bf16 v[16:19], v[156:159], v[218:221], v[16:19]
	v_mfma_f32_16x16x32_bf16 v[12:15], v[168:171], v[218:221], v[12:15]
	s_setprio 0
	s_setprio 1
	v_mfma_f32_16x16x32_bf16 v[56:59], v[172:175], v[188:191], 0
	v_mfma_f32_16x16x32_bf16 v[52:55], v[180:183], v[188:191], 0
	v_mfma_f32_16x16x32_bf16 v[40:43], v[172:175], v[196:199], 0
	v_mfma_f32_16x16x32_bf16 v[36:39], v[180:183], v[196:199], 0
	v_mfma_f32_16x16x32_bf16 v[24:27], v[172:175], v[204:207], 0
	v_mfma_f32_16x16x32_bf16 v[20:23], v[180:183], v[204:207], 0
	v_mfma_f32_16x16x32_bf16 v[8:11], v[172:175], v[214:217], 0
	v_mfma_f32_16x16x32_bf16 v[4:7], v[180:183], v[214:217], 0
	v_mfma_f32_16x16x32_bf16 v[56:59], v[176:179], v[192:195], v[56:59]
	v_mfma_f32_16x16x32_bf16 v[52:55], v[184:187], v[192:195], v[52:55]
	v_mfma_f32_16x16x32_bf16 v[40:43], v[176:179], v[200:203], v[40:43]
	v_mfma_f32_16x16x32_bf16 v[36:39], v[184:187], v[200:203], v[36:39]
	v_mfma_f32_16x16x32_bf16 v[24:27], v[176:179], v[210:213], v[24:27]
	v_mfma_f32_16x16x32_bf16 v[20:23], v[184:187], v[210:213], v[20:23]
	v_mfma_f32_16x16x32_bf16 v[8:11], v[176:179], v[218:221], v[8:11]
	v_mfma_f32_16x16x32_bf16 v[4:7], v[184:187], v[218:221], v[4:7]
	s_setprio 0
	s_barrier
	s_add_i32 s9, 0, 0x18000
	v_add_u32_e32 v2, s9, v147
	s_add_i32 s29, 0, 0x1c000
	ds_read_b128 v[152:155], v2
	ds_read_b128 v[156:159], v2 offset:1024
	ds_read_b128 v[160:163], v2 offset:2048
	ds_read_b128 v[168:171], v2 offset:3072
	v_add_u32_e32 v2, s29, v147
	ds_read_b128 v[172:175], v2
	ds_read_b128 v[176:179], v2 offset:1024
	ds_read_b128 v[180:183], v2 offset:2048
	ds_read_b128 v[184:187], v2 offset:3072
	s_add_u32 s22, s22, s16
	s_addc_u32 s23, s23, 0
	s_mov_b32 m0, s49
	ds_read_b128 v[188:191], v150 offset:32768
	ds_read_b128 v[192:195], v150 offset:33792
	ds_read_b128 v[196:199], v150 offset:34816
	ds_read_b128 v[200:203], v150 offset:35840
	ds_read_b128 v[204:207], v150 offset:36864
	ds_read_b128 v[210:213], v150 offset:37888
	ds_read_b128 v[214:217], v150 offset:38912
	ds_read_b128 v[218:221], v150 offset:39936
	global_load_lds_dwordx4 v138, s[22:23]
	s_mov_b32 m0, s50
	s_nop 0
	global_load_lds_dwordx4 v134, s[22:23]
	s_waitcnt vmcnt(8)
	s_waitcnt lgkmcnt(0)
	s_barrier
	s_setprio 1
	s_waitcnt lgkmcnt(0)
	v_mfma_f32_16x16x32_bf16 v[128:131], v[152:155], v[188:191], v[128:131]
	v_mfma_f32_16x16x32_bf16 v[124:127], v[160:163], v[188:191], v[124:127]
	v_mfma_f32_16x16x32_bf16 v[112:115], v[152:155], v[196:199], v[112:115]
	v_mfma_f32_16x16x32_bf16 v[108:111], v[160:163], v[196:199], v[108:111]
	v_mfma_f32_16x16x32_bf16 v[96:99], v[152:155], v[204:207], v[96:99]
	v_mfma_f32_16x16x32_bf16 v[92:95], v[160:163], v[204:207], v[92:95]
	v_mfma_f32_16x16x32_bf16 v[80:83], v[152:155], v[214:217], v[80:83]
	v_mfma_f32_16x16x32_bf16 v[76:79], v[160:163], v[214:217], v[76:79]
	v_mfma_f32_16x16x32_bf16 v[128:131], v[156:159], v[192:195], v[128:131]
	v_mfma_f32_16x16x32_bf16 v[124:127], v[168:171], v[192:195], v[124:127]
	v_mfma_f32_16x16x32_bf16 v[112:115], v[156:159], v[200:203], v[112:115]
	v_mfma_f32_16x16x32_bf16 v[108:111], v[168:171], v[200:203], v[108:111]
	v_mfma_f32_16x16x32_bf16 v[96:99], v[156:159], v[210:213], v[96:99]
	v_mfma_f32_16x16x32_bf16 v[92:95], v[168:171], v[210:213], v[92:95]
	v_mfma_f32_16x16x32_bf16 v[80:83], v[156:159], v[218:221], v[80:83]
	v_mfma_f32_16x16x32_bf16 v[76:79], v[168:171], v[218:221], v[76:79]
	s_setprio 0
	s_setprio 1
	v_mfma_f32_16x16x32_bf16 v[120:123], v[172:175], v[188:191], v[120:123]
	v_mfma_f32_16x16x32_bf16 v[116:119], v[180:183], v[188:191], v[116:119]
	v_mfma_f32_16x16x32_bf16 v[104:107], v[172:175], v[196:199], v[104:107]
	v_mfma_f32_16x16x32_bf16 v[100:103], v[180:183], v[196:199], v[100:103]
	v_mfma_f32_16x16x32_bf16 v[88:91], v[172:175], v[204:207], v[88:91]
	v_mfma_f32_16x16x32_bf16 v[84:87], v[180:183], v[204:207], v[84:87]
	v_mfma_f32_16x16x32_bf16 v[72:75], v[172:175], v[214:217], v[72:75]
	v_mfma_f32_16x16x32_bf16 v[68:71], v[180:183], v[214:217], v[68:71]
	v_mfma_f32_16x16x32_bf16 v[120:123], v[176:179], v[192:195], v[120:123]
	v_mfma_f32_16x16x32_bf16 v[116:119], v[184:187], v[192:195], v[116:119]
	v_mfma_f32_16x16x32_bf16 v[104:107], v[176:179], v[200:203], v[104:107]
	v_mfma_f32_16x16x32_bf16 v[100:103], v[184:187], v[200:203], v[100:103]
	v_mfma_f32_16x16x32_bf16 v[88:91], v[176:179], v[210:213], v[88:91]
	v_mfma_f32_16x16x32_bf16 v[84:87], v[184:187], v[210:213], v[84:87]
	v_mfma_f32_16x16x32_bf16 v[72:75], v[176:179], v[218:221], v[72:75]
	v_mfma_f32_16x16x32_bf16 v[68:71], v[184:187], v[218:221], v[68:71]
	s_setprio 0
	s_barrier
	s_add_i32 s9, s9, s26
	s_mov_b32 m0, s9
	ds_read_b128 v[188:191], v150 offset:49152
	ds_read_b128 v[192:195], v150 offset:50176
	ds_read_b128 v[196:199], v150 offset:51200
	ds_read_b128 v[200:203], v150 offset:52224
	ds_read_b128 v[204:207], v150 offset:53248
	ds_read_b128 v[210:213], v150 offset:54272
	ds_read_b128 v[214:217], v150 offset:55296
	ds_read_b128 v[218:221], v150 offset:56320
	s_sub_u32 s34, s34, s16
	s_subb_u32 s35, s35, 0
	s_add_u32 s34, s34, 0x80
	s_addc_u32 s35, s35, 0
	global_load_lds_dwordx4 v136, s[34:35]
	s_add_i32 m0, s9, 0x2000
	s_add_i32 s9, s29, s26
	global_load_lds_dwordx4 v132, s[34:35]
	s_mov_b32 m0, s9
	s_nop 0
	s_add_u32 s34, s34, s16
	s_addc_u32 s35, s35, 0
	global_load_lds_dwordx4 v136, s[34:35]
	s_add_i32 m0, s9, 0x2000
	s_nop 0
	global_load_lds_dwordx4 v132, s[34:35]
	s_mov_b32 m0, s53
	s_nop 0
	s_sub_u32 s22, s22, s16
	s_subb_u32 s23, s23, 0
	s_add_u32 s22, s22, s100
	s_addc_u32 s23, s23, 0
	global_load_lds_dwordx4 v138, s[22:23]
	s_mov_b32 m0, s54
	s_nop 0
	global_load_lds_dwordx4 v134, s[22:23]
	s_waitcnt vmcnt(8)
	s_waitcnt lgkmcnt(0)
	s_barrier
	s_setprio 1
	s_waitcnt lgkmcnt(0)
	v_mfma_f32_16x16x32_bf16 v[64:67], v[152:155], v[188:191], v[64:67]
	v_mfma_f32_16x16x32_bf16 v[60:63], v[160:163], v[188:191], v[60:63]
	v_mfma_f32_16x16x32_bf16 v[48:51], v[152:155], v[196:199], v[48:51]
	v_mfma_f32_16x16x32_bf16 v[44:47], v[160:163], v[196:199], v[44:47]
	v_mfma_f32_16x16x32_bf16 v[32:35], v[152:155], v[204:207], v[32:35]
	v_mfma_f32_16x16x32_bf16 v[28:31], v[160:163], v[204:207], v[28:31]
	v_mfma_f32_16x16x32_bf16 v[16:19], v[152:155], v[214:217], v[16:19]
	v_mfma_f32_16x16x32_bf16 v[12:15], v[160:163], v[214:217], v[12:15]
	v_mfma_f32_16x16x32_bf16 v[64:67], v[156:159], v[192:195], v[64:67]
	v_mfma_f32_16x16x32_bf16 v[60:63], v[168:171], v[192:195], v[60:63]
	v_mfma_f32_16x16x32_bf16 v[48:51], v[156:159], v[200:203], v[48:51]
	v_mfma_f32_16x16x32_bf16 v[44:47], v[168:171], v[200:203], v[44:47]
	v_mfma_f32_16x16x32_bf16 v[32:35], v[156:159], v[210:213], v[32:35]
	v_mfma_f32_16x16x32_bf16 v[28:31], v[168:171], v[210:213], v[28:31]
	v_mfma_f32_16x16x32_bf16 v[16:19], v[156:159], v[218:221], v[16:19]
	v_mfma_f32_16x16x32_bf16 v[12:15], v[168:171], v[218:221], v[12:15]
	s_setprio 0
	s_setprio 1
	v_mfma_f32_16x16x32_bf16 v[56:59], v[172:175], v[188:191], v[56:59]
	v_mfma_f32_16x16x32_bf16 v[52:55], v[180:183], v[188:191], v[52:55]
	v_mfma_f32_16x16x32_bf16 v[40:43], v[172:175], v[196:199], v[40:43]
	v_mfma_f32_16x16x32_bf16 v[36:39], v[180:183], v[196:199], v[36:39]
	v_mfma_f32_16x16x32_bf16 v[24:27], v[172:175], v[204:207], v[24:27]
	v_mfma_f32_16x16x32_bf16 v[20:23], v[180:183], v[204:207], v[20:23]
	v_mfma_f32_16x16x32_bf16 v[8:11], v[172:175], v[214:217], v[8:11]
	v_mfma_f32_16x16x32_bf16 v[4:7], v[180:183], v[214:217], v[4:7]
	v_mfma_f32_16x16x32_bf16 v[56:59], v[176:179], v[192:195], v[56:59]
	v_mfma_f32_16x16x32_bf16 v[52:55], v[184:187], v[192:195], v[52:55]
	v_mfma_f32_16x16x32_bf16 v[40:43], v[176:179], v[200:203], v[40:43]
	v_mfma_f32_16x16x32_bf16 v[36:39], v[184:187], v[200:203], v[36:39]
	v_mfma_f32_16x16x32_bf16 v[24:27], v[176:179], v[210:213], v[24:27]
	v_mfma_f32_16x16x32_bf16 v[20:23], v[184:187], v[210:213], v[20:23]
	v_mfma_f32_16x16x32_bf16 v[8:11], v[176:179], v[218:221], v[8:11]
	v_mfma_f32_16x16x32_bf16 v[4:7], v[184:187], v[218:221], v[4:7]
	s_setprio 0
	s_barrier
	s_add_u32 s2, s2, s98
	s_addc_u32 s3, s3, 0
	s_add_u32 s7, s7, 0x100
	s_addc_u32 s8, s8, 0
	s_cmp_ge_u32 s28, s51
	s_mov_b32 s9, s28
	s_cbranch_scc0 .LBB0_832
	s_branch .Lpeel_done_832

.Lpeel_done_832:
	s_and_b64 vcc, exec, s[18:19]
	s_cbranch_vccz .LBB0_835
	s_barrier
